# SGU mixer: next item's statistics and V-tile prefetch issued before the MFMA chain, W_s tile right after it
# speedup vs baseline: 1.0042x; 1.0042x over previous
.LBB0_131:
	s_or_b64 exec, exec, s[26:27]
	s_waitcnt lgkmcnt(0)
	s_barrier
	ds_read_b64 v[2:3], v171
	s_waitcnt vmcnt(20)
	v_lshlrev_b32_e32 v5, 16, v70
	v_lshlrev_b32_e32 v4, 16, v66
	v_and_b32_e32 v7, 0xffff0000, v70
	v_and_b32_e32 v6, 0xffff0000, v66
	s_waitcnt lgkmcnt(0)
	v_pk_mul_f32 v[4:5], v[2:3], v[4:5]
	v_pk_mul_f32 v[6:7], v[2:3], v[6:7]
	v_cvt_pk_bf16_f32 v4, v4, v5
	v_cvt_pk_bf16_f32 v5, v6, v7
	ds_write2_b32 v176, v4, v5 offset0:128 offset1:196
	v_lshlrev_b32_e32 v5, 16, v71
	v_lshlrev_b32_e32 v4, 16, v67
	v_and_b32_e32 v7, 0xffff0000, v71
	v_and_b32_e32 v6, 0xffff0000, v67
	v_pk_mul_f32 v[4:5], v[2:3], v[4:5]
	v_pk_mul_f32 v[6:7], v[2:3], v[6:7]
	v_cvt_pk_bf16_f32 v4, v4, v5
	v_cvt_pk_bf16_f32 v5, v6, v7
	v_add_u32_e32 v8, 0x400, v176
	ds_write2_b32 v8, v4, v5 offset0:8 offset1:76
	v_lshlrev_b32_e32 v5, 16, v72
	v_lshlrev_b32_e32 v4, 16, v68
	v_and_b32_e32 v7, 0xffff0000, v72
	v_and_b32_e32 v6, 0xffff0000, v68
	v_pk_mul_f32 v[4:5], v[2:3], v[4:5]
	v_pk_mul_f32 v[6:7], v[2:3], v[6:7]
	v_cvt_pk_bf16_f32 v4, v4, v5
	v_cvt_pk_bf16_f32 v5, v6, v7
	ds_write2_b32 v8, v4, v5 offset0:144 offset1:212
	v_lshlrev_b32_e32 v5, 16, v73
	v_lshlrev_b32_e32 v4, 16, v69
	v_and_b32_e32 v7, 0xffff0000, v73
	v_and_b32_e32 v6, 0xffff0000, v69
	v_pk_mul_f32 v[4:5], v[2:3], v[4:5]
	v_pk_mul_f32 v[6:7], v[2:3], v[6:7]
	v_cvt_pk_bf16_f32 v4, v4, v5
	v_cvt_pk_bf16_f32 v5, v6, v7
	v_add_u32_e32 v6, 0x800, v176
	ds_write2_b32 v6, v4, v5 offset0:24 offset1:92
	s_waitcnt vmcnt(18)
	v_lshlrev_b32_e32 v5, 16, v78
	v_lshlrev_b32_e32 v4, 16, v74
	v_and_b32_e32 v7, 0xffff0000, v78
	v_and_b32_e32 v6, 0xffff0000, v74
	v_pk_mul_f32 v[4:5], v[2:3], v[4:5]
	v_pk_mul_f32 v[6:7], v[2:3], v[6:7]
	v_cvt_pk_bf16_f32 v4, v4, v5
	v_cvt_pk_bf16_f32 v5, v6, v7
	ds_write2_b32 v177, v4, v5 offset0:128 offset1:196
	v_lshlrev_b32_e32 v5, 16, v79
	v_lshlrev_b32_e32 v4, 16, v75
	v_and_b32_e32 v7, 0xffff0000, v79
	v_and_b32_e32 v6, 0xffff0000, v75
	v_pk_mul_f32 v[4:5], v[2:3], v[4:5]
	v_pk_mul_f32 v[6:7], v[2:3], v[6:7]
	v_cvt_pk_bf16_f32 v4, v4, v5
	v_cvt_pk_bf16_f32 v5, v6, v7
	v_add_u32_e32 v8, 0x400, v177
	ds_write2_b32 v8, v4, v5 offset0:8 offset1:76
	v_lshlrev_b32_e32 v5, 16, v80
	v_lshlrev_b32_e32 v4, 16, v76
	v_and_b32_e32 v7, 0xffff0000, v80
	v_and_b32_e32 v6, 0xffff0000, v76
	v_pk_mul_f32 v[4:5], v[2:3], v[4:5]
	v_pk_mul_f32 v[6:7], v[2:3], v[6:7]
	v_cvt_pk_bf16_f32 v4, v4, v5
	v_cvt_pk_bf16_f32 v5, v6, v7
	ds_write2_b32 v8, v4, v5 offset0:144 offset1:212
	v_lshlrev_b32_e32 v5, 16, v81
	v_lshlrev_b32_e32 v4, 16, v77
	v_and_b32_e32 v7, 0xffff0000, v81
	v_and_b32_e32 v6, 0xffff0000, v77
	v_pk_mul_f32 v[4:5], v[2:3], v[4:5]
	v_pk_mul_f32 v[2:3], v[2:3], v[6:7]
	v_cvt_pk_bf16_f32 v4, v4, v5
	v_cvt_pk_bf16_f32 v2, v2, v3
	v_add_u32_e32 v3, 0x800, v177
	ds_write2_b32 v3, v4, v2 offset0:24 offset1:92
	s_waitcnt lgkmcnt(0)
	s_barrier
	s_add_i32 s100, s3, s12
	s_cmpk_lt_i32 s100, 0x800
	s_cbranch_scc1 .Lsgu_pfa
	s_waitcnt vmcnt(0)
	s_branch .Lsgu_pfa_done
.Lsgu_pfa:
	v_mov_b32_e32 v191, 0
	s_add_i32 s11, s62, s10
	s_and_b32 s10, s11, 0xffffff80
	v_or_b32_e32 v192, s10, v166
	v_ashrrev_i32_e32 v193, 31, v192
	v_readlane_b32 s16, v252, 15
	v_lshlrev_b64 v[192:193], 7, v[192:193]
	v_readlane_b32 s17, v252, 16
	v_readlane_b32 s20, v252, 31
	v_readlane_b32 s21, v252, 32
	v_lshl_add_u64 v[192:193], s[16:17], 0, v[192:193]
	global_load_dwordx4 v[34:37], v[192:193], off offset:48
	global_load_dwordx4 v[38:41], v[192:193], off offset:32
	global_load_dwordx4 v[42:45], v[192:193], off offset:16
	global_load_dwordx4 v[46:49], v[192:193], off
	global_load_dwordx4 v[50:53], v[192:193], off offset:112
	global_load_dwordx4 v[54:57], v[192:193], off offset:96
	global_load_dwordx4 v[58:61], v[192:193], off offset:80
	global_load_dwordx4 v[62:65], v[192:193], off offset:64
	v_or_b32_e32 v192, s10, v167
	v_ashrrev_i32_e32 v193, 31, v192
	v_lshlrev_b64 v[194:195], 12, v[192:193]
	v_or_b32_e32 v192, 1, v192
	v_readfirstlane_b32 s10, v164
	s_add_i32 s16, s22, s6
	v_ashrrev_i32_e32 v193, 31, v192
	s_lshr_b32 s10, s10, 1
	s_and_b32 s6, s16, 0x780
	v_lshlrev_b64 v[192:193], 12, v[192:193]
	s_and_b32 s10, s10, 0x60
	v_lshl_add_u64 v[194:195], s[20:21], 0, v[194:195]
	s_lshl_b32 s18, s6, 1
	s_mov_b32 s19, s85
	v_lshl_add_u64 v[192:193], s[20:21], 0, v[192:193]
	v_or_b32_e32 v190, s10, v165
	v_lshl_add_u64 v[194:195], v[194:195], 0, s[18:19]
	v_lshl_add_u64 v[192:193], v[192:193], 0, s[18:19]
	v_or_b32_e32 v190, s6, v190
	v_lshl_add_u64 v[196:197], v[194:195], 0, v[146:147]
	v_lshl_add_u64 v[198:199], v[192:193], 0, v[146:147]
	v_lshl_add_u64 v[194:195], v[194:195], 0, v[148:149]
	v_lshl_add_u64 v[192:193], v[192:193], 0, v[148:149]
	v_lshlrev_b32_e32 v190, 8, v190
	global_load_dwordx4 v[66:69], v[196:197], off
	global_load_dwordx4 v[70:73], v[198:199], off
	global_load_dwordx4 v[74:77], v[194:195], off
	global_load_dwordx4 v[78:81], v[192:193], off
.Lsgu_pfa_done:
	ds_read_b128 v[2:5], v183 offset:512
	ds_read_b128 v[186:189], v183 offset:544
	s_waitcnt vmcnt(29) lgkmcnt(1)
	v_mfma_f32_32x32x16_bf16 v[18:33], v[82:85], v[2:5], 0
	ds_read_b128 v[2:5], v183 offset:9216
	s_andn2_b64 vcc, exec, s[56:57]
	s_waitcnt vmcnt(28) lgkmcnt(1)
	v_mfma_f32_32x32x16_bf16 v[18:33], v[86:89], v[186:189], v[18:33]
	ds_read_b128 v[186:189], v183 offset:9248
	s_waitcnt lgkmcnt(1)
	v_mfma_f32_32x32x16_bf16 v[2:17], v[82:85], v[2:5], 0
	s_waitcnt lgkmcnt(0)
	v_mfma_f32_32x32x16_bf16 v[2:17], v[86:89], v[186:189], v[2:17]
	s_cbranch_vccnz .LBB0_133
	ds_read_b128 v[186:189], v183 offset:576
	s_waitcnt vmcnt(27) lgkmcnt(0)
	v_mfma_f32_32x32x16_bf16 v[18:33], v[90:93], v[186:189], v[18:33]
	ds_read_b128 v[186:189], v183 offset:9280
	s_waitcnt lgkmcnt(0)
	v_mfma_f32_32x32x16_bf16 v[2:17], v[90:93], v[186:189], v[2:17]

.LBB0_138:
	ds_read_b128 v[186:189], v183 offset:736
	s_waitcnt vmcnt(22) lgkmcnt(0)
	v_mfma_f32_32x32x16_bf16 v[18:33], v[110:113], v[186:189], v[18:33]
	ds_read_b128 v[186:189], v183 offset:9440
	s_waitcnt lgkmcnt(0)
	v_mfma_f32_32x32x16_bf16 v[2:17], v[110:113], v[186:189], v[2:17]
.LBB0_139:
	s_add_i32 s100, s3, s12
	s_cmpk_lt_i32 s100, 0x800
	s_cbranch_scc0 .Lsgu_epi
	v_lshl_add_u64 v[192:193], v[152:153], 0, v[190:191]
	global_load_dwordx4 v[82:85], v[192:193], off
	global_load_dwordx4 v[86:89], v[192:193], off offset:32
	global_load_dwordx4 v[90:93], v[192:193], off offset:64
	global_load_dwordx4 v[94:97], v[192:193], off offset:96
	global_load_dwordx4 v[98:101], v[192:193], off offset:128
	global_load_dwordx4 v[102:105], v[192:193], off offset:160
	global_load_dwordx4 v[106:109], v[192:193], off offset:192
	global_load_dwordx4 v[110:113], v[192:193], off offset:224
.Lsgu_epi:
	s_waitcnt vmcnt(23)
	s_nop 7
	v_fma_f32 v18, v184, v18, v142
	s_nop 1
	v_fma_f32 v2, v0, v2, v142
	v_add_u32_e32 v142, 0x9000, v178
	v_fma_f32 v19, v184, v19, v143
	ds_write2_b32 v142, v18, v2 offset1:32
	v_fma_f32 v2, v0, v3, v143
	v_fma_f32 v20, v184, v20, v144
	v_fma_f32 v21, v184, v21, v145
	ds_write2_b32 v142, v19, v2 offset0:132 offset1:164
	v_fma_f32 v2, v0, v4, v144
	v_add_u32_e32 v3, 0x9400, v178
	v_fmac_f32_e32 v145, v0, v5
	s_waitcnt vmcnt(22)
	v_fma_f32 v22, v184, v22, v138
	ds_write2_b32 v3, v20, v2 offset0:8 offset1:40
	ds_write2_b32 v3, v21, v145 offset0:140 offset1:172
	v_fma_f32 v2, v0, v6, v138
	v_add_u32_e32 v3, 0xa000, v178
	v_fma_f32 v23, v184, v23, v139
	ds_write2_b32 v3, v22, v2 offset0:32 offset1:64
	v_fma_f32 v2, v0, v7, v139
	v_fma_f32 v24, v184, v24, v140
	v_fma_f32 v25, v184, v25, v141
	ds_write2_b32 v3, v23, v2 offset0:164 offset1:196
	v_fma_f32 v2, v0, v8, v140
	v_add_u32_e32 v3, 0xa400, v178
	v_fmac_f32_e32 v141, v0, v9
	s_waitcnt vmcnt(21)
	v_fma_f32 v26, v184, v26, v134
	ds_write2_b32 v3, v24, v2 offset0:40 offset1:72
	ds_write2_b32 v3, v25, v141 offset0:172 offset1:204
	v_fma_f32 v2, v0, v10, v134
	v_add_u32_e32 v3, 0xb000, v178
	v_fma_f32 v27, v184, v27, v135
	ds_write2_b32 v3, v26, v2 offset0:64 offset1:96
	v_fma_f32 v2, v0, v11, v135
	v_fma_f32 v28, v184, v28, v136
	v_fma_f32 v29, v184, v29, v137
	ds_write2_b32 v3, v27, v2 offset0:196 offset1:228
	v_fma_f32 v2, v0, v12, v136
	v_add_u32_e32 v3, 0xb400, v178
	v_fmac_f32_e32 v137, v0, v13
	s_waitcnt vmcnt(20)
	v_fma_f32 v30, v184, v30, v130
	ds_write2_b32 v3, v28, v2 offset0:72 offset1:104
	ds_write2_b32 v3, v29, v137 offset0:204 offset1:236
	v_fma_f32 v2, v0, v14, v130
	v_add_u32_e32 v3, 0xc000, v178
	s_add_i32 s3, s3, s12
	v_fma_f32 v31, v184, v31, v131
	ds_write2_b32 v3, v30, v2 offset0:96 offset1:128
	v_fma_f32 v2, v0, v15, v131
	v_add_u32_e32 v3, 0xc200, v178
	s_cmpk_gt_i32 s3, 0x7ff
	v_fma_f32 v32, v184, v32, v132
	v_fma_f32 v33, v184, v33, v133
	ds_write2_b32 v3, v31, v2 offset0:100 offset1:132
	v_fma_f32 v2, v0, v16, v132
	v_add_u32_e32 v3, 0xc400, v178
	v_fmac_f32_e32 v133, v0, v17
	v_add_u32_e32 v0, 0xc600, v178
	s_cselect_b64 s[42:43], -1, 0
	s_cmpk_lt_i32 s3, 0x800
	s_mov_b64 s[26:27], -1
	ds_write2_b32 v3, v32, v2 offset0:104 offset1:136
	ds_write2_b32 v0, v33, v133 offset0:108 offset1:140
	s_cbranch_scc1 .LBB0_141
	s_add_i32 s11, s10, s62
	s_add_i32 s16, s6, s22
	s_mov_b64 s[26:27], 0
.LBB0_141:
	s_andn2_b64 vcc, exec, s[26:27]
	s_cbranch_vccnz .LBB0_128
	s_branch .LBB0_128
.LBB0_143:
	ds_read_b128 v[186:189], v183 offset:608
	s_waitcnt vmcnt(26) lgkmcnt(0)
	v_mfma_f32_32x32x16_bf16 v[18:33], v[94:97], v[186:189], v[18:33]
	ds_read_b128 v[186:189], v183 offset:9312
	s_waitcnt lgkmcnt(0)
	v_mfma_f32_32x32x16_bf16 v[2:17], v[94:97], v[186:189], v[2:17]
	s_andn2_b64 vcc, exec, s[86:87]
	s_cbranch_vccnz .LBB0_135
.LBB0_144:
	ds_read_b128 v[186:189], v183 offset:640
	s_waitcnt vmcnt(25) lgkmcnt(0)
	v_mfma_f32_32x32x16_bf16 v[18:33], v[98:101], v[186:189], v[18:33]
	ds_read_b128 v[186:189], v183 offset:9344
	s_waitcnt lgkmcnt(0)
	v_mfma_f32_32x32x16_bf16 v[2:17], v[98:101], v[186:189], v[2:17]
	s_andn2_b64 vcc, exec, s[88:89]
	s_cbranch_vccnz .LBB0_136
.LBB0_145:
	ds_read_b128 v[186:189], v183 offset:672
	s_waitcnt vmcnt(24) lgkmcnt(0)
	v_mfma_f32_32x32x16_bf16 v[18:33], v[102:105], v[186:189], v[18:33]
	ds_read_b128 v[186:189], v183 offset:9376
	s_waitcnt lgkmcnt(0)
	v_mfma_f32_32x32x16_bf16 v[2:17], v[102:105], v[186:189], v[2:17]
	v_cndmask_b32_e64 v185, 0, 1, s[90:91]
	v_cmp_ne_u32_e64 s[42:43], 1, v185
	s_andn2_b64 vcc, exec, s[90:91]
	s_cbranch_vccnz .LBB0_137
.LBB0_146:
	ds_read_b128 v[186:189], v183 offset:704
	s_waitcnt vmcnt(23) lgkmcnt(0)
	v_mfma_f32_32x32x16_bf16 v[18:33], v[106:109], v[186:189], v[18:33]
	ds_read_b128 v[186:189], v183 offset:9408
	s_waitcnt lgkmcnt(0)
	v_mfma_f32_32x32x16_bf16 v[2:17], v[106:109], v[186:189], v[2:17]
	s_and_b64 vcc, exec, s[42:43]
	s_cbranch_vccz .LBB0_138
	s_branch .LBB0_139
